# P8 down-projection residual epilogue de-serialised: the 4 loads of each row group issued together into spare registers, in-order vmcnt(3) waits (32 round trips -> 8); on top of v71
# speedup vs baseline: 1.0088x; 1.0088x over previous
.LBB0_1733:
	v_lshl_add_u32 v138, s55, 8, v140
	v_lshl_or_b32 v134, s54, 8, v142
	v_ashrrev_i32_e32 v139, 31, v138
	v_ashrrev_i32_e32 v135, 31, v134
	v_lshlrev_b64 v[136:137], 14, v[138:139]
	v_lshl_add_u64 v[146:147], s[6:7], 0, v[136:137]
	v_lshlrev_b64 v[136:137], 2, v[134:135]
	v_lshl_add_u64 v[134:135], v[146:147], 0, v[136:137]
	global_load_dwordx4 v[200:203], v[134:135], off
	global_load_dwordx4 v[204:207], v[134:135], off offset:64
	global_load_dwordx4 v[208:211], v[134:135], off offset:512
	global_load_dwordx4 v[212:215], v[134:135], off offset:576
	s_mov_b64 s[2:3], -1
	s_waitcnt vmcnt(3)
	v_pk_add_f32 v[128:129], v[128:129], v[202:203]
	v_pk_add_f32 v[126:127], v[126:127], v[200:201]
	global_store_dwordx4 v[134:135], v[126:129], off
	s_waitcnt vmcnt(3)
	v_pk_add_f32 v[124:125], v[124:125], v[206:207]
	v_pk_add_f32 v[122:123], v[122:123], v[204:205]
	global_store_dwordx4 v[134:135], v[122:125], off offset:64
	s_waitcnt vmcnt(3)
	v_pk_add_f32 v[120:121], v[120:121], v[210:211]
	v_pk_add_f32 v[118:119], v[118:119], v[208:209]
	global_store_dwordx4 v[134:135], v[118:121], off offset:512
	s_waitcnt vmcnt(3)
	v_pk_add_f32 v[112:113], v[112:113], v[214:215]
	v_pk_add_f32 v[110:111], v[110:111], v[212:213]
	global_store_dwordx4 v[134:135], v[110:113], off offset:576
	s_nop 1
	v_or_b32_e32 v110, 16, v138
	v_ashrrev_i32_e32 v111, 31, v110
	v_lshlrev_b64 v[110:111], 14, v[110:111]
	v_lshl_add_u64 v[110:111], s[6:7], 0, v[110:111]
	v_lshl_add_u64 v[118:119], v[110:111], 0, v[136:137]
	global_load_dwordx4 v[200:203], v[118:119], off
	global_load_dwordx4 v[204:207], v[118:119], off offset:64
	global_load_dwordx4 v[208:211], v[118:119], off offset:512
	global_load_dwordx4 v[212:215], v[118:119], off offset:576
	s_waitcnt vmcnt(3)
	v_pk_add_f32 v[112:113], v[116:117], v[202:203]
	v_pk_add_f32 v[110:111], v[114:115], v[200:201]
	global_store_dwordx4 v[118:119], v[110:113], off
	s_waitcnt vmcnt(3)
	v_pk_add_f32 v[108:109], v[108:109], v[206:207]
	v_pk_add_f32 v[106:107], v[106:107], v[204:205]
	global_store_dwordx4 v[118:119], v[106:109], off offset:64
	s_waitcnt vmcnt(3)
	v_pk_add_f32 v[104:105], v[104:105], v[210:211]
	v_pk_add_f32 v[102:103], v[102:103], v[208:209]
	global_store_dwordx4 v[118:119], v[102:105], off offset:512
	s_waitcnt vmcnt(3)
	v_pk_add_f32 v[100:101], v[100:101], v[214:215]
	v_pk_add_f32 v[98:99], v[98:99], v[212:213]
	global_store_dwordx4 v[118:119], v[98:101], off offset:576
	s_nop 1
	v_or_b32_e32 v98, 32, v138
	v_ashrrev_i32_e32 v99, 31, v98
	v_lshlrev_b64 v[98:99], 14, v[98:99]
	v_lshl_add_u64 v[98:99], s[6:7], 0, v[98:99]
	v_lshl_add_u64 v[102:103], v[98:99], 0, v[136:137]
	global_load_dwordx4 v[200:203], v[102:103], off
	global_load_dwordx4 v[204:207], v[102:103], off offset:64
	global_load_dwordx4 v[208:211], v[102:103], off offset:512
	global_load_dwordx4 v[212:215], v[102:103], off offset:576
	s_waitcnt vmcnt(3)
	v_pk_add_f32 v[96:97], v[96:97], v[202:203]
	v_pk_add_f32 v[94:95], v[94:95], v[200:201]
	global_store_dwordx4 v[102:103], v[94:97], off
	s_waitcnt vmcnt(3)
	v_pk_add_f32 v[92:93], v[92:93], v[206:207]
	v_pk_add_f32 v[90:91], v[90:91], v[204:205]
	global_store_dwordx4 v[102:103], v[90:93], off offset:64
	s_waitcnt vmcnt(3)
	v_pk_add_f32 v[88:89], v[88:89], v[210:211]
	v_pk_add_f32 v[86:87], v[86:87], v[208:209]
	global_store_dwordx4 v[102:103], v[86:89], off offset:512
	s_waitcnt vmcnt(3)
	v_pk_add_f32 v[84:85], v[84:85], v[214:215]
	v_pk_add_f32 v[82:83], v[82:83], v[212:213]
	global_store_dwordx4 v[102:103], v[82:85], off offset:576
	s_nop 1
	v_or_b32_e32 v82, 48, v138
	v_ashrrev_i32_e32 v83, 31, v82
	v_lshlrev_b64 v[82:83], 14, v[82:83]
	v_lshl_add_u64 v[82:83], s[6:7], 0, v[82:83]
	v_lshl_add_u64 v[86:87], v[82:83], 0, v[136:137]
	global_load_dwordx4 v[200:203], v[86:87], off
	global_load_dwordx4 v[204:207], v[86:87], off offset:64
	global_load_dwordx4 v[208:211], v[86:87], off offset:512
	global_load_dwordx4 v[212:215], v[86:87], off offset:576
	s_waitcnt vmcnt(3)
	v_pk_add_f32 v[80:81], v[80:81], v[202:203]
	v_pk_add_f32 v[78:79], v[78:79], v[200:201]
	global_store_dwordx4 v[86:87], v[78:81], off
	s_waitcnt vmcnt(3)
	v_pk_add_f32 v[76:77], v[76:77], v[206:207]
	v_pk_add_f32 v[74:75], v[74:75], v[204:205]
	global_store_dwordx4 v[86:87], v[74:77], off offset:64
	s_waitcnt vmcnt(3)
	v_pk_add_f32 v[72:73], v[72:73], v[210:211]
	v_pk_add_f32 v[70:71], v[70:71], v[208:209]
	global_store_dwordx4 v[86:87], v[70:73], off offset:512
	s_waitcnt vmcnt(3)
	v_pk_add_f32 v[68:69], v[68:69], v[214:215]
	v_add_co_u32_e32 v72, vcc, s48, v134
	v_pk_add_f32 v[66:67], v[66:67], v[212:213]
	s_nop 0
	v_addc_co_u32_e32 v73, vcc, 0, v135, vcc
	global_store_dwordx4 v[86:87], v[66:69], off offset:576
	global_load_dwordx4 v[200:203], v[72:73], off
	global_load_dwordx4 v[204:207], v[72:73], off offset:64
	global_load_dwordx4 v[208:211], v[72:73], off offset:512
	global_load_dwordx4 v[212:215], v[72:73], off offset:576
	v_lshl_add_u64 v[70:71], v[134:135], 0, s[12:13]
	s_waitcnt vmcnt(3)
	v_pk_add_f32 v[64:65], v[64:65], v[202:203]
	v_pk_add_f32 v[62:63], v[62:63], v[200:201]
	global_store_dwordx4 v[72:73], v[62:65], off
	s_waitcnt vmcnt(3)
	v_pk_add_f32 v[60:61], v[60:61], v[206:207]
	v_pk_add_f32 v[58:59], v[58:59], v[204:205]
	global_store_dwordx4 v[70:71], v[58:61], off offset:64
	s_waitcnt vmcnt(3)
	v_pk_add_f32 v[56:57], v[56:57], v[210:211]
	v_pk_add_f32 v[54:55], v[54:55], v[208:209]
	global_store_dwordx4 v[70:71], v[54:57], off offset:512
	s_waitcnt vmcnt(3)
	v_pk_add_f32 v[52:53], v[52:53], v[214:215]
	v_add_co_u32_e32 v56, vcc, s49, v134
	v_pk_add_f32 v[50:51], v[50:51], v[212:213]
	s_nop 0
	v_addc_co_u32_e32 v57, vcc, 0, v135, vcc
	global_store_dwordx4 v[70:71], v[50:53], off offset:576
	global_load_dwordx4 v[200:203], v[56:57], off
	global_load_dwordx4 v[204:207], v[56:57], off offset:64
	global_load_dwordx4 v[208:211], v[56:57], off offset:512
	global_load_dwordx4 v[212:215], v[56:57], off offset:576
	v_lshl_add_u64 v[54:55], v[134:135], 0, s[14:15]
	s_waitcnt vmcnt(3)
	v_pk_add_f32 v[48:49], v[48:49], v[202:203]
	v_pk_add_f32 v[46:47], v[46:47], v[200:201]
	global_store_dwordx4 v[56:57], v[46:49], off
	s_waitcnt vmcnt(3)
	v_pk_add_f32 v[44:45], v[44:45], v[206:207]
	v_pk_add_f32 v[42:43], v[42:43], v[204:205]
	global_store_dwordx4 v[54:55], v[42:45], off offset:64
	s_waitcnt vmcnt(3)
	v_pk_add_f32 v[40:41], v[40:41], v[210:211]
	v_pk_add_f32 v[38:39], v[38:39], v[208:209]
	global_store_dwordx4 v[54:55], v[38:41], off offset:512
	s_waitcnt vmcnt(3)
	v_pk_add_f32 v[36:37], v[36:37], v[214:215]
	v_add_co_u32_e32 v40, vcc, s50, v134
	v_pk_add_f32 v[34:35], v[34:35], v[212:213]
	s_nop 0
	v_addc_co_u32_e32 v41, vcc, 0, v135, vcc
	global_store_dwordx4 v[54:55], v[34:37], off offset:576
	global_load_dwordx4 v[200:203], v[40:41], off
	global_load_dwordx4 v[204:207], v[40:41], off offset:64
	global_load_dwordx4 v[208:211], v[40:41], off offset:512
	global_load_dwordx4 v[212:215], v[40:41], off offset:576
	v_lshl_add_u64 v[38:39], v[134:135], 0, s[16:17]
	s_waitcnt vmcnt(3)
	v_pk_add_f32 v[32:33], v[32:33], v[202:203]
	v_pk_add_f32 v[30:31], v[30:31], v[200:201]
	global_store_dwordx4 v[40:41], v[30:33], off
	s_waitcnt vmcnt(3)
	v_pk_add_f32 v[28:29], v[28:29], v[206:207]
	v_pk_add_f32 v[26:27], v[26:27], v[204:205]
	global_store_dwordx4 v[38:39], v[26:29], off offset:64
	s_waitcnt vmcnt(3)
	v_pk_add_f32 v[24:25], v[24:25], v[210:211]
	v_pk_add_f32 v[22:23], v[22:23], v[208:209]
	global_store_dwordx4 v[38:39], v[22:25], off offset:512
	s_waitcnt vmcnt(3)
	v_pk_add_f32 v[20:21], v[20:21], v[214:215]
	v_add_co_u32_e32 v24, vcc, s51, v134
	v_pk_add_f32 v[18:19], v[18:19], v[212:213]
	s_nop 0
	v_addc_co_u32_e32 v25, vcc, 0, v135, vcc
	global_store_dwordx4 v[38:39], v[18:21], off offset:576
	global_load_dwordx4 v[200:203], v[24:25], off
	global_load_dwordx4 v[204:207], v[24:25], off offset:64
	global_load_dwordx4 v[208:211], v[24:25], off offset:512
	global_load_dwordx4 v[212:215], v[24:25], off offset:576
	s_and_b64 vcc, exec, s[0:1]
	v_lshl_add_u64 v[18:19], v[134:135], 0, s[18:19]
	s_waitcnt vmcnt(3)
	v_pk_add_f32 v[16:17], v[16:17], v[202:203]
	v_pk_add_f32 v[14:15], v[14:15], v[200:201]
	global_store_dwordx4 v[24:25], v[14:17], off
	s_waitcnt vmcnt(3)
	v_pk_add_f32 v[12:13], v[12:13], v[206:207]
	v_pk_add_f32 v[10:11], v[10:11], v[204:205]
	global_store_dwordx4 v[18:19], v[10:13], off offset:64
	s_waitcnt vmcnt(3)
	v_pk_add_f32 v[8:9], v[8:9], v[210:211]
	v_pk_add_f32 v[6:7], v[6:7], v[208:209]
	global_store_dwordx4 v[18:19], v[6:9], off offset:512
	s_waitcnt vmcnt(3)
	v_pk_add_f32 v[4:5], v[4:5], v[214:215]
	v_pk_add_f32 v[2:3], v[2:3], v[212:213]
	global_store_dwordx4 v[18:19], v[2:5], off offset:576
	s_cbranch_vccnz .LBB0_1716
	s_andn2_b64 vcc, exec, s[4:5]
	s_cbranch_vccnz .LBB0_1715
	s_barrier
	s_branch .LBB0_1715
